# attention: flag loads issued first and checked after the Q and first K loads are in flight (barrier moved behind them)
# baseline (speedup 1.0000x reference)
.Lat_pu:
	s_and_b32 s18, s25, 3
	s_lshr_b32 s20, s25, 3
	v_readlane_b32 s21, v255, 21
	s_sub_i32 s29, 63, s20
	s_lshl_b32 s6, s18, 2
	s_add_u32 s27, s22, s6
	s_addc_u32 s28, s23, 0
	s_lshr_b32 s21, s21, 2
	s_cmp_eq_u32 s21, 0
	s_cselect_b32 s35, s29, s20
	s_andn2_b64 vcc, exec, s[14:15]
	s_cbranch_vccnz .Lat_noflag
	s_lshl_b32 s8, s29, 6
	s_add_u32 s8, s27, s8
	s_addc_u32 s9, s28, 0
	s_lshl_b32 s10, s20, 6
	s_add_u32 s10, s27, s10
	s_addc_u32 s11, s28, 0
	global_load_dword v130, v1, s[8:9] sc1
	global_load_dword v131, v1, s[8:9] offset:16 sc1
	global_load_dword v132, v1, s[8:9] offset:32 sc1
	global_load_dword v133, v1, s[8:9] offset:48 sc1
	global_load_dword v134, v1, s[10:11] sc1
	global_load_dword v135, v1, s[10:11] offset:16 sc1
	global_load_dword v136, v1, s[10:11] offset:32 sc1
	global_load_dword v137, v1, s[10:11] offset:48 sc1
.Lat_noflag:
	s_lshl_b32 s8, s18, 21
	s_or_b32 s8, s8, s24
	v_readlane_b32 s6, v255, 34
	v_readlane_b32 s7, v255, 35
	v_readlane_b32 s10, v255, 32
	v_readlane_b32 s11, v255, 33
	v_readlane_b32 s30, v255, 41
	v_readlane_b32 s31, v255, 42
	s_add_u32 s6, s6, s8
	s_addc_u32 s7, s7, 0
	s_add_u32 s10, s10, s8
	s_addc_u32 s11, s11, 0
	s_lshl_b32 s20, s18, 7
	s_lshl_b32 s21, s35, 1
	s_add_i32 s20, s20, s21
	s_lshl_b32 s20, s20, 14
	s_add_u32 s20, s30, s20
	s_addc_u32 s21, s31, 0
	s_add_i32 s19, s35, 1
	s_lshl_b32 s9, s19, 1
	s_and_b64 s[30:31], s[12:13], exec
	s_cselect_b32 s8, 0, s19
	s_cselect_b32 s19, s19, s9
	s_add_i32 s9, s19, -1
	s_lshl_b32 s35, s35, 1
	s_lshl_b32 s26, s18, 12
	s_lshl_b32 s34, s35, 5
	s_add_i32 s18, s34, s26
	v_or_b32_e32 v0, s18, v138
	v_mad_u64_u32 v[34:35], vcc, v0, s33, v[148:149]
	s_mov_b32 s30, 0x30000
	s_mov_b32 s31, 0
	global_load_dwordx4 v[82:85], v[34:35], off offset:2560
	global_load_dwordx4 v[86:89], v[34:35], off offset:2592
	global_load_dwordx4 v[90:93], v[34:35], off offset:2624
	global_load_dwordx4 v[94:97], v[34:35], off offset:2656
	v_lshl_add_u64 v[36:37], v[34:35], 0, s[30:31]
	global_load_dwordx4 v[114:117], v[36:37], off offset:2560
	global_load_dwordx4 v[118:121], v[36:37], off offset:2592
	global_load_dwordx4 v[122:125], v[36:37], off offset:2624
	global_load_dwordx4 v[126:129], v[36:37], off offset:2656
	v_lshlrev_b32_e32 v175, 2, v139
	v_lshl_add_u32 v175, v138, 5, v175
	v_lshlrev_b32_e32 v176, 2, v138
	v_add_u32_e32 v177, 0x4000, v176
	s_mov_b32 s100, s8
	s_lshl_b32 s27, s8, 12
	s_add_u32 s28, s6, s27
	s_addc_u32 s29, s7, 0
	global_load_dwordx4 v[66:69], v175, s[28:29]
	global_load_dwordx4 v[70:73], v175, s[28:29] offset:1024
	global_load_dwordx4 v[74:77], v175, s[28:29] offset:2048
	global_load_dwordx4 v[78:81], v175, s[28:29] offset:3072
	s_andn2_b64 vcc, exec, s[14:15]
	s_cbranch_vccnz .Lat_nospin
	s_waitcnt vmcnt(0)
	v_min3_u32 v130, v130, v131, v132
	v_min3_u32 v133, v133, v134, v135
	v_min3_u32 v130, v130, v136, v137
	v_min_u32_e32 v130, v130, v133
	s_nop 0
	v_readfirstlane_b32 s26, v130
	s_cmp_gt_u32 s26, 7
	s_cbranch_scc1 .Lat_spin_done
	s_and_b32 s26, s25, 3
	s_lshl_b32 s26, s26, 2
	s_add_u32 s28, s22, s26
	s_addc_u32 s29, s23, 0
	s_lshr_b32 s26, s25, 3
	s_sub_i32 s34, 63, s26
	s_lshl_b32 s26, s26, 6
	s_lshl_b32 s34, s34, 6
	s_add_u32 s30, s28, s34
	s_addc_u32 s31, s29, 0
	s_add_u32 s28, s28, s26
	s_addc_u32 s29, s29, 0
	s_mov_b32 s34, 0x400000
.Lat_spin:
	s_sleep 4
	global_load_dword v130, v1, s[30:31] sc1
	global_load_dword v131, v1, s[30:31] offset:16 sc1
	global_load_dword v132, v1, s[30:31] offset:32 sc1
	global_load_dword v133, v1, s[30:31] offset:48 sc1
	global_load_dword v134, v1, s[28:29] sc1
	global_load_dword v135, v1, s[28:29] offset:16 sc1
	global_load_dword v136, v1, s[28:29] offset:32 sc1
	global_load_dword v137, v1, s[28:29] offset:48 sc1
	s_waitcnt vmcnt(0)
	v_min3_u32 v130, v130, v131, v132
	v_min3_u32 v133, v133, v134, v135
	v_min3_u32 v130, v130, v136, v137
	v_min_u32_e32 v130, v130, v133
	s_nop 0
	v_readfirstlane_b32 s26, v130
	s_cmp_gt_u32 s26, 7
	s_cbranch_scc1 .Lat_spin_done
	s_add_i32 s34, s34, -1
	s_cmp_eq_u32 s34, 0
	s_cbranch_scc0 .Lat_spin

.Lat_nospin:
	s_barrier
	s_lshl_b32 s34, s8, 7
	s_add_u32 s30, s20, s34
	s_addc_u32 s31, s21, 0
	global_load_dword v173, v176, s[30:31] sc1
	global_load_dword v174, v177, s[30:31] sc1
	s_add_u32 s28, s10, s27
	s_addc_u32 s29, s11, 0
	global_load_dwordx4 v[98:101], v175, s[28:29]
	global_load_dwordx4 v[102:105], v175, s[28:29] offset:1024
	global_load_dwordx4 v[106:109], v175, s[28:29] offset:2048
	global_load_dwordx4 v[110:113], v175, s[28:29] offset:3072
	s_add_i32 s26, s8, 1
	s_min_i32 s26, s26, s9
	s_lshl_b32 s27, s26, 12
	s_add_u32 s28, s6, s27
	s_addc_u32 s29, s7, 0
	global_load_dwordx4 v[130:133], v175, s[28:29]
	global_load_dwordx4 v[134:137], v175, s[28:29] offset:1024
	global_load_dwordx4 v[182:185], v175, s[28:29] offset:2048
	global_load_dwordx4 v[186:189], v175, s[28:29] offset:3072
	v_mov_b32_e32 v2, 0
	v_mov_b32_e32 v3, 0
	v_mov_b32_e32 v4, 0
	v_mov_b32_e32 v5, 0
	v_mov_b32_e32 v6, 0
	v_mov_b32_e32 v7, 0
	v_mov_b32_e32 v8, 0
	v_mov_b32_e32 v9, 0
	v_mov_b32_e32 v10, 0
	v_mov_b32_e32 v11, 0
	v_mov_b32_e32 v12, 0
	v_mov_b32_e32 v13, 0
	v_mov_b32_e32 v14, 0
	v_mov_b32_e32 v15, 0
	v_mov_b32_e32 v16, 0
	v_mov_b32_e32 v17, 0
	v_mov_b32_e32 v18, 0
	v_mov_b32_e32 v19, 0
	v_mov_b32_e32 v20, 0
	v_mov_b32_e32 v21, 0
	v_mov_b32_e32 v22, 0
	v_mov_b32_e32 v23, 0
	v_mov_b32_e32 v24, 0
	v_mov_b32_e32 v25, 0
	v_mov_b32_e32 v26, 0
	v_mov_b32_e32 v27, 0
	v_mov_b32_e32 v28, 0
	v_mov_b32_e32 v29, 0
	v_mov_b32_e32 v30, 0
	v_mov_b32_e32 v31, 0
	v_mov_b32_e32 v32, 0
	v_mov_b32_e32 v33, 0
	v_mov_b32_e32 v198, 0
	v_mov_b32_e32 v199, 0
	v_mov_b32_e32 v200, 0
	v_mov_b32_e32 v201, 0
	v_mov_b32_e32 v202, 0
	v_mov_b32_e32 v203, 0
	v_mov_b32_e32 v204, 0
	v_mov_b32_e32 v205, 0
	v_mov_b32_e32 v206, 0
	v_mov_b32_e32 v207, 0
	v_mov_b32_e32 v208, 0
	v_mov_b32_e32 v209, 0
	v_mov_b32_e32 v210, 0
	v_mov_b32_e32 v211, 0
	v_mov_b32_e32 v212, 0
	v_mov_b32_e32 v213, 0
	v_mov_b32_e32 v220, 0
	v_mov_b32_e32 v221, 0
	v_mov_b32_e32 v222, 0
	v_mov_b32_e32 v223, 0
	v_mov_b32_e32 v224, 0
	v_mov_b32_e32 v225, 0
	v_mov_b32_e32 v226, 0
	v_mov_b32_e32 v227, 0
	v_mov_b32_e32 v228, 0
	v_mov_b32_e32 v229, 0
	v_mov_b32_e32 v230, 0
	v_mov_b32_e32 v231, 0
	v_mov_b32_e32 v232, 0
	v_mov_b32_e32 v233, 0
	v_mov_b32_e32 v234, 0
	v_mov_b32_e32 v235, 0
	v_mov_b32_e32 v167, 0
	v_mov_b32_e32 v169, 0
	v_mov_b32_e32 v168, 0
	v_mov_b32_e32 v170, 0
	v_mov_b32_e32 v140, 0
	v_mov_b32_e32 v141, 0
	v_mov_b32_e32 v142, 0
	v_mov_b32_e32 v143, 0
	v_mov_b32_e32 v152, 0
	v_mov_b32_e32 v153, 0
	v_mov_b32_e32 v154, 0
	v_mov_b32_e32 v155, 0
	v_mov_b32_e32 v214, 0
	v_mov_b32_e32 v215, 0
	v_mov_b32_e32 v216, 0
	v_mov_b32_e32 v217, 0
	v_mov_b32_e32 v236, 0
	v_mov_b32_e32 v237, 0
	v_mov_b32_e32 v238, 0
	v_mov_b32_e32 v239, 0
	v_mov_b32_e32 v50, 0
	v_mov_b32_e32 v51, 0
	v_mov_b32_e32 v52, 0
	v_mov_b32_e32 v53, 0
	v_mov_b32_e32 v54, 0
	v_mov_b32_e32 v55, 0
	v_mov_b32_e32 v56, 0
	v_mov_b32_e32 v57, 0
	s_waitcnt vmcnt(10)
	v_mfma_f32_32x32x16_bf16 v[34:49], v[66:69], v[82:85], 0
	v_mfma_f32_32x32x16_bf16 v[34:49], v[70:73], v[86:89], v[34:49]
	v_mfma_f32_32x32x16_bf16 v[34:49], v[74:77], v[90:93], v[34:49]
	v_mfma_f32_32x32x16_bf16 v[34:49], v[78:81], v[94:97], v[34:49]
